# attention K/V LDS-DMA issued at top of each steady-state step, on top of epilogue hoists
# baseline (speedup 1.0000x reference)
; #define WAIT_BAR(N) asm volatile("s_waitcnt vmcnt(" #N ") lgkmcnt(0)\n\ts_barrier":::"memory")
;   #define RESC() do{}while(0)
;   #define ROT() do{sl_prev=sl_cur;sl_cur=sl_next;sl_next=(sl_next==(NSLOT-1)*SLOTB)?0:sl_next+SLOTB;}while(0)
; template<int THRL> __device__ __forceinline__ void attn_unit(int b,int h,int qb,int t0,float cqv,float mfix,const float*__restrict__ cf,float cref,unsigned*counter,const bf16*Q,const bf16*__restrict__ K,const bf16*__restrict__ V,bf16*O,const bf16*__restrict__ G,char*shm){
;     ...
;     STEP(pB0,pB1,pA0,pA1,t,true,true,true);     WAIT_BAR(2); RESC(); ROT();
.LBB0_871:
	s_mov_b32 s54, s72
	s_mov_b32 s18, s19
	s_mov_b32 s16, s59
	v_lshl_add_u64 v[250:251], v[214:215], 0, s[50:51]
	s_add_i32 s98, s59, s68
	s_mov_b32 s99, m0
	s_mov_b32 m0, s98
	v_lshl_add_u64 v[252:253], v[212:213], 0, s[50:51]
	s_nop 0
	global_load_lds_dwordx4 v[250:251], off
	s_add_i32 s98, s72, s69
	s_mov_b32 m0, s98
	s_nop 0
	global_load_lds_dwordx4 v[252:253], off
	s_mov_b32 m0, s99
	v_add_u32_e32 v34, s17, v235
	ds_read_b64_tr_b16 v[190:191], v34 offset:24576
	ds_read_b64_tr_b16 v[192:193], v34 offset:25088
	v_add_f32_e32 v35, v64, v65
	v_add_f32_e32 v35, v66, v35
	v_add_f32_e32 v35, v67, v35
	v_add_f32_e32 v35, v68, v35
	v_add_f32_e32 v35, v69, v35
	s_waitcnt lgkmcnt(9)
	v_mfma_f32_32x32x16_bf16 v[80:95], v[172:175], v[124:127], 0
	v_cvt_pk_bf16_f32 v174, v64, v65
	v_cvt_pk_bf16_f32 v175, v66, v67
	ds_read_b64_tr_b16 v[194:195], v34 offset:28672
	ds_read_b64_tr_b16 v[196:197], v34 offset:29184
	v_add_f32_e32 v35, v70, v35
	v_add_f32_e32 v35, v71, v35
	v_add_f32_e32 v35, v72, v35
	v_add_f32_e32 v35, v73, v35
	v_cvt_pk_bf16_f32 v176, v68, v69
	v_cvt_pk_bf16_f32 v177, v70, v71
	s_waitcnt lgkmcnt(10)
	v_mfma_f32_32x32x16_bf16 v[96:111], v[164:167], v[124:127], 0
	ds_read_b64_tr_b16 v[164:165], v34 offset:25600
	ds_read_b64_tr_b16 v[166:167], v34 offset:26112
	v_add_f32_e32 v35, v74, v35
	v_add_f32_e32 v35, v75, v35
	v_add_f32_e32 v35, v76, v35
	v_add_f32_e32 v35, v77, v35
	v_cvt_pk_bf16_f32 v178, v72, v73
	v_cvt_pk_bf16_f32 v179, v74, v75
	s_waitcnt lgkmcnt(11)
	v_mfma_f32_32x32x16_bf16 v[80:95], v[168:171], v[120:123], v[80:95]
	ds_read_b64_tr_b16 v[168:169], v34 offset:29696
	ds_read_b64_tr_b16 v[170:171], v34 offset:30208
	v_add_f32_e32 v35, v78, v35
	v_add_f32_e32 v35, v79, v35
	v_add_f32_e32 v35, v48, v35
	v_add_f32_e32 v35, v49, v35
	v_cvt_pk_bf16_f32 v180, v76, v77
	v_cvt_pk_bf16_f32 v181, v78, v79
	s_waitcnt lgkmcnt(12)
	v_mfma_f32_32x32x16_bf16 v[96:111], v[160:163], v[120:123], v[96:111]
	ds_read_b64_tr_b16 v[160:161], v34 offset:26624
	ds_read_b64_tr_b16 v[162:163], v34 offset:27136
	v_add_f32_e32 v35, v50, v35
	v_add_f32_e32 v35, v51, v35
	v_add_f32_e32 v35, v52, v35
	v_add_f32_e32 v35, v53, v35
	v_cvt_pk_bf16_f32 v182, v48, v49
	v_cvt_pk_bf16_f32 v183, v50, v51
	s_waitcnt lgkmcnt(13)
	v_mfma_f32_32x32x16_bf16 v[80:95], v[156:159], v[116:119], v[80:95]
	ds_read_b64_tr_b16 v[156:157], v34 offset:30720
	ds_read_b64_tr_b16 v[158:159], v34 offset:31232
	v_add_f32_e32 v35, v54, v35
	v_add_f32_e32 v35, v55, v35
	v_add_f32_e32 v35, v56, v35
	v_add_f32_e32 v35, v57, v35
	v_cvt_pk_bf16_f32 v184, v52, v53
	v_cvt_pk_bf16_f32 v185, v54, v55
	s_waitcnt lgkmcnt(14)
	v_mfma_f32_32x32x16_bf16 v[96:111], v[152:155], v[116:119], v[96:111]
	ds_read_b64_tr_b16 v[152:153], v34 offset:27648
	ds_read_b64_tr_b16 v[154:155], v34 offset:28160
	v_add_f32_e32 v35, v58, v35
	v_add_f32_e32 v35, v59, v35
	v_add_f32_e32 v35, v60, v35
	v_add_f32_e32 v35, v61, v35
	v_cvt_pk_bf16_f32 v186, v56, v57
	v_cvt_pk_bf16_f32 v187, v58, v59
	s_waitcnt lgkmcnt(14)
	v_mfma_f32_32x32x16_bf16 v[80:95], v[148:151], v[112:115], v[80:95]
	ds_read_b64_tr_b16 v[148:149], v34 offset:31744
	ds_read_b64_tr_b16 v[150:151], v34 offset:32256
	v_add_f32_e32 v34, v62, v35
	v_add_f32_e32 v34, v63, v34
	v_add_f32_e32 v172, 0, v34
	v_cvt_pk_bf16_f32 v188, v60, v61
	v_cvt_pk_bf16_f32 v189, v62, v63
	v_mfma_f32_32x32x16_bf16 v[96:111], v[144:147], v[112:115], v[96:111]
	ds_read_b128 v[34:37], v33 offset:128
	ds_read_b128 v[38:41], v33
	ds_read_b128 v[42:45], v33 offset:32
	s_waitcnt lgkmcnt(2)
	v_sub_f32_e32 v34, v206, v34
	s_nop 2
	v_add_f32_e32 v70, v96, v34
	s_waitcnt lgkmcnt(1)
	v_sub_f32_e32 v34, v206, v39
	v_add_f32_e32 v51, v81, v34
	v_sub_f32_e32 v34, v206, v35
	v_add_f32_e32 v71, v97, v34
	v_sub_f32_e32 v34, v206, v40
	v_add_f32_e32 v52, v82, v34
	v_sub_f32_e32 v34, v206, v36
	v_add_f32_e32 v72, v98, v34
	v_sub_f32_e32 v34, v206, v41
	v_add_f32_e32 v53, v83, v34
	v_sub_f32_e32 v34, v206, v37
	v_add_f32_e32 v73, v99, v34
	ds_read_b128 v[34:37], v33 offset:160
	v_sub_f32_e32 v38, v206, v38
	v_add_f32_e32 v50, v80, v38
	s_waitcnt lgkmcnt(1)
	v_pk_add_f32 v[38:39], v[206:207], v[42:43] neg_lo:[0,1] neg_hi:[0,1]
	s_waitcnt lgkmcnt(0)
	v_pk_add_f32 v[34:35], v[206:207], v[34:35] neg_lo:[0,1] neg_hi:[0,1]
	v_pk_add_f32 v[54:55], v[84:85], v[38:39]
	v_pk_add_f32 v[38:39], v[100:101], v[34:35]
	v_pk_add_f32 v[34:35], v[206:207], v[44:45] neg_lo:[0,1] neg_hi:[0,1]
	s_nop 0
	v_pk_add_f32 v[56:57], v[86:87], v[34:35]
	v_pk_add_f32 v[34:35], v[206:207], v[36:37] neg_lo:[0,1] neg_hi:[0,1]
	s_nop 0
	v_pk_add_f32 v[40:41], v[102:103], v[34:35]
	ds_read_b128 v[34:37], v33 offset:64
	ds_read_b128 v[42:45], v33 offset:192
	s_waitcnt lgkmcnt(1)
	v_pk_add_f32 v[34:35], v[206:207], v[34:35] neg_lo:[0,1] neg_hi:[0,1]
	s_nop 0
	v_pk_add_f32 v[58:59], v[88:89], v[34:35]
	s_waitcnt lgkmcnt(0)
	v_pk_add_f32 v[34:35], v[206:207], v[42:43] neg_lo:[0,1] neg_hi:[0,1]
	s_nop 0
	v_pk_add_f32 v[42:43], v[104:105], v[34:35]
	v_pk_add_f32 v[34:35], v[206:207], v[36:37] neg_lo:[0,1] neg_hi:[0,1]
	s_nop 0
	v_pk_add_f32 v[60:61], v[90:91], v[34:35]
	v_pk_add_f32 v[34:35], v[206:207], v[44:45] neg_lo:[0,1] neg_hi:[0,1]
	s_nop 0
	v_pk_add_f32 v[44:45], v[106:107], v[34:35]
	ds_read_b128 v[34:37], v33 offset:96
	ds_read_b128 v[46:49], v33 offset:224
	s_waitcnt lgkmcnt(1)
	v_pk_add_f32 v[34:35], v[206:207], v[34:35] neg_lo:[0,1] neg_hi:[0,1]
	s_nop 0
	v_pk_add_f32 v[62:63], v[92:93], v[34:35]
	s_waitcnt lgkmcnt(0)
	v_pk_add_f32 v[34:35], v[206:207], v[46:47] neg_lo:[0,1] neg_hi:[0,1]
	s_nop 0
	v_pk_add_f32 v[46:47], v[108:109], v[34:35]
	v_pk_add_f32 v[34:35], v[206:207], v[36:37] neg_lo:[0,1] neg_hi:[0,1]
	s_nop 0
	v_pk_add_f32 v[64:65], v[94:95], v[34:35]
	v_pk_add_f32 v[34:35], v[206:207], v[48:49] neg_lo:[0,1] neg_hi:[0,1]
	s_nop 0
	v_pk_add_f32 v[48:49], v[110:111], v[34:35]
	v_exp_f32_e32 v50, v50
	v_exp_f32_e32 v51, v51
	v_exp_f32_e32 v52, v52
	v_exp_f32_e32 v53, v53
	s_nop 0
	v_exp_f32_e32 v54, v54
	v_exp_f32_e32 v55, v55
	v_exp_f32_e32 v56, v56
	v_exp_f32_e32 v57, v57
	v_add_u32_e32 v74, s54, v233
	ds_read_b128 v[66:69], v74
	ds_read_b128 v[82:85], v74 offset:512
	v_exp_f32_e32 v58, v58
	v_exp_f32_e32 v59, v59
	v_exp_f32_e32 v60, v60
	v_exp_f32_e32 v61, v61
	ds_read_b128 v[102:105], v74 offset:2048
	ds_read_b128 v[132:135], v74 offset:2560
	v_exp_f32_e32 v62, v62
	v_exp_f32_e32 v63, v63
	v_exp_f32_e32 v64, v64
	v_exp_f32_e32 v65, v65
	ds_read_b128 v[140:143], v74 offset:4096
	ds_read_b128 v[236:239], v74 offset:4608
	v_exp_f32_e32 v34, v70
	v_exp_f32_e32 v35, v71
	v_exp_f32_e32 v36, v72
	v_exp_f32_e32 v37, v73
	ds_read_b128 v[240:243], v74 offset:6144
	ds_read_b128 v[244:247], v74 offset:6656
	v_exp_f32_e32 v38, v38
	v_exp_f32_e32 v39, v39
	v_exp_f32_e32 v40, v40
	v_exp_f32_e32 v41, v41
	s_nop 0
	v_exp_f32_e32 v42, v42
	v_exp_f32_e32 v43, v43
	v_exp_f32_e32 v44, v44
	v_exp_f32_e32 v45, v45
	s_nop 0
	v_exp_f32_e32 v46, v46
	v_exp_f32_e32 v47, v47
	v_exp_f32_e32 v48, v48
	v_exp_f32_e32 v49, v49
	s_waitcnt vmcnt(2) lgkmcnt(0)
	s_barrier
; #define WAIT_BAR(N) asm volatile("s_waitcnt vmcnt(" #N ") lgkmcnt(0)\n\ts_barrier":::"memory")
;   #define RESC() do{}while(0)
;   #define ROT() do{sl_prev=sl_cur;sl_cur=sl_next;sl_next=(sl_next==(NSLOT-1)*SLOTB)?0:sl_next+SLOTB;}while(0)
; template<int THRL> __device__ __forceinline__ void attn_unit(int b,int h,int qb,int t0,float cqv,float mfix,const float*__restrict__ cf,float cref,unsigned*counter,const bf16*Q,const bf16*__restrict__ K,const bf16*__restrict__ V,bf16*O,const bf16*__restrict__ G,char*shm){
;     ...
;     STEP(pA0,pA1,pB0,pB1,t+1,true,true,true);   WAIT_BAR(2); RESC(); ROT();
	s_add_i32 s14, s72, 0x2000
	s_cmpk_lg_i32 s72, 0x4000
	s_cselect_b32 s59, s14, 0
	s_add_i32 s98, s72, s68
	s_mov_b32 s99, m0
	s_mov_b32 m0, s98
	s_nop 0
	global_load_lds_dwordx4 v[214:215], off
	s_add_i32 s98, s59, s69
	s_mov_b32 m0, s98
	s_nop 0
	global_load_lds_dwordx4 v[212:213], off
	s_mov_b32 m0, s99
	v_add_u32_e32 v110, s16, v235
	ds_read_b64_tr_b16 v[198:199], v110 offset:24576
	ds_read_b64_tr_b16 v[200:201], v110 offset:25088
	v_add_f32_e32 v70, v50, v51
	v_add_f32_e32 v70, v52, v70
	v_add_f32_e32 v70, v53, v70
	v_add_f32_e32 v70, v54, v70
	v_add_f32_e32 v86, v55, v70
	s_waitcnt lgkmcnt(9)
	v_mfma_f32_32x32x16_bf16 v[66:81], v[66:69], v[124:127], 0
	v_cvt_pk_bf16_f32 v50, v50, v51
	v_mov_b64_e32 v[128:129], v[174:175]
	v_mov_b64_e32 v[130:131], v[176:177]
	v_mov_b32_e32 v128, v50
	v_cvt_pk_bf16_f32 v129, v52, v53
	ds_read_b64_tr_b16 v[106:107], v110 offset:28672
	ds_read_b64_tr_b16 v[108:109], v110 offset:29184
	v_add_f32_e32 v50, v56, v86
	v_add_f32_e32 v50, v57, v50
	v_add_f32_e32 v50, v58, v50
	v_add_f32_e32 v50, v59, v50
	v_cvt_pk_bf16_f32 v130, v54, v55
	v_cvt_pk_bf16_f32 v131, v56, v57
	s_waitcnt lgkmcnt(10)
	v_mfma_f32_32x32x16_bf16 v[82:97], v[82:85], v[124:127], 0
	ds_read_b64_tr_b16 v[98:99], v110 offset:25600
	ds_read_b64_tr_b16 v[100:101], v110 offset:26112
	s_waitcnt lgkmcnt(11)
	v_mfma_f32_32x32x16_bf16 v[66:81], v[102:105], v[120:123], v[66:81]
	v_add_f32_e32 v50, v60, v50
	v_add_f32_e32 v50, v61, v50
	v_add_f32_e32 v50, v62, v50
	v_cvt_pk_bf16_f32 v51, v58, v59
	v_mov_b64_e32 v[136:137], v[178:179]
	v_add_f32_e32 v50, v63, v50
	v_mov_b64_e32 v[138:139], v[180:181]
	v_mov_b32_e32 v136, v51
	v_cvt_pk_bf16_f32 v137, v60, v61
	ds_read_b64_tr_b16 v[102:103], v110 offset:29696
	ds_read_b64_tr_b16 v[104:105], v110 offset:30208
	v_add_f32_e32 v50, v64, v50
	v_add_f32_e32 v50, v65, v50
	v_add_f32_e32 v50, v34, v50
	v_add_f32_e32 v50, v35, v50
	v_cvt_pk_bf16_f32 v138, v62, v63
	v_cvt_pk_bf16_f32 v139, v64, v65
	s_waitcnt lgkmcnt(12)
	v_mfma_f32_32x32x16_bf16 v[82:97], v[132:135], v[120:123], v[82:97]
	ds_read_b64_tr_b16 v[144:145], v110 offset:26624
	ds_read_b64_tr_b16 v[146:147], v110 offset:27136
	s_waitcnt lgkmcnt(13)
	v_mfma_f32_32x32x16_bf16 v[66:81], v[140:143], v[116:119], v[66:81]
	v_add_f32_e32 v50, v36, v50
	v_add_f32_e32 v50, v37, v50
	v_add_f32_e32 v50, v38, v50
	v_cvt_pk_bf16_f32 v34, v34, v35
	v_mov_b64_e32 v[132:133], v[182:183]
	v_add_f32_e32 v50, v39, v50
	v_mov_b64_e32 v[134:135], v[184:185]
	v_mov_b32_e32 v132, v34
	v_cvt_pk_bf16_f32 v133, v36, v37
	ds_read_b64_tr_b16 v[34:35], v110 offset:30720
	ds_read_b64_tr_b16 v[36:37], v110 offset:31232
	v_add_f32_e32 v50, v40, v50
	v_add_f32_e32 v50, v41, v50
	v_add_f32_e32 v50, v42, v50
	v_add_f32_e32 v50, v43, v50
	v_cvt_pk_bf16_f32 v134, v38, v39
	v_cvt_pk_bf16_f32 v135, v40, v41
	s_waitcnt lgkmcnt(14)
	v_mfma_f32_32x32x16_bf16 v[82:97], v[236:239], v[116:119], v[82:97]
	ds_read_b64_tr_b16 v[38:39], v110 offset:27648
	ds_read_b64_tr_b16 v[40:41], v110 offset:28160
	s_waitcnt lgkmcnt(14)
	v_mfma_f32_32x32x16_bf16 v[66:81], v[240:243], v[112:115], v[66:81]
	v_add_f32_e32 v50, v44, v50
	v_add_f32_e32 v50, v45, v50
	v_add_f32_e32 v50, v46, v50
	v_cvt_pk_bf16_f32 v42, v42, v43
	v_mov_b64_e32 v[140:141], v[186:187]
	v_add_f32_e32 v50, v47, v50
	v_mov_b64_e32 v[142:143], v[188:189]
	v_mov_b32_e32 v140, v42
	v_cvt_pk_bf16_f32 v141, v44, v45
	ds_read_b64_tr_b16 v[42:43], v110 offset:31744
	ds_read_b64_tr_b16 v[44:45], v110 offset:32256
	v_add_f32_e32 v50, v48, v50
	v_add_f32_e32 v50, v49, v50
	v_add_f32_e32 v64, 0, v50
	v_cvt_pk_bf16_f32 v142, v46, v47
	v_cvt_pk_bf16_f32 v143, v48, v49
	v_mfma_f32_32x32x16_bf16 v[82:97], v[244:247], v[112:115], v[82:97]
	v_mfma_f32_32x32x16_bf16 v[0:15], v[174:177], v[190:193], v[0:15]
	ds_read_b128 v[50:53], v33 offset:384
	ds_read_b128 v[54:57], v33 offset:256
	ds_read_b128 v[58:61], v33 offset:288
	v_add_f32_e32 v32, v32, v172
	v_add_f32_e32 v32, v32, v64
	v_mfma_f32_32x32x16_bf16 v[16:31], v[174:177], v[194:197], v[16:31]
	s_waitcnt lgkmcnt(1)
	v_sub_f32_e32 v46, v206, v54
	v_sub_f32_e32 v47, v206, v55
	v_add_f32_e32 v48, v66, v46
	v_sub_f32_e32 v46, v206, v50
	v_add_f32_e32 v49, v67, v47
	v_sub_f32_e32 v47, v206, v51
	v_sub_f32_e32 v50, v206, v56
	v_mfma_f32_32x32x16_bf16 v[0:15], v[178:181], v[164:167], v[0:15]
	v_sub_f32_e32 v51, v206, v57
	s_waitcnt lgkmcnt(0)
; #define WAIT_BAR(N) asm volatile("s_waitcnt vmcnt(" #N ") lgkmcnt(0)\n\ts_barrier":::"memory")
;   #define RESC() do{}while(0)
;   #define ROT() do{sl_prev=sl_cur;sl_cur=sl_next;sl_next=(sl_next==(NSLOT-1)*SLOTB)?0:sl_next+SLOTB;}while(0)
; template<int THRL> __device__ __forceinline__ void attn_unit(int b,int h,int qb,int t0,float cqv,float mfix,const float*__restrict__ cf,float cref,unsigned*counter,const bf16*Q,const bf16*__restrict__ K,const bf16*__restrict__ V,bf16*O,const bf16*__restrict__ G,char*shm){
;     ...
;   int t=1;
;     ...
;   for(;t+5<NT;t+=2){
;     STEP(pB0,pB1,pA0,pA1,t,true,true,true);     WAIT_BAR(2); RESC(); ROT();
;     STEP(pA0,pA1,pB0,pB1,t+1,true,true,true);   WAIT_BAR(2); RESC(); ROT();
;   }
	v_add_f32_e64 v56, v206, -v58
	v_add_f32_e64 v57, v207, -v59
	v_add_f32_e32 v66, v68, v50
	v_add_f32_e32 v67, v69, v51
	v_pk_add_f32 v[68:69], v[70:71], v[56:57]
	v_pk_add_f32 v[56:57], v[206:207], v[60:61] neg_lo:[0,1] neg_hi:[0,1]
	v_sub_f32_e32 v50, v206, v52
	v_mfma_f32_32x32x16_bf16 v[16:31], v[178:181], v[168:171], v[16:31]
	v_sub_f32_e32 v51, v206, v53
	ds_read_b128 v[52:55], v33 offset:416
	v_add_f32_e64 v70, v72, v56
	v_add_f32_e64 v71, v73, v57
	ds_read_b128 v[56:59], v33 offset:320
	ds_read_b128 v[60:63], v33 offset:448
	v_add_f32_e32 v46, v82, v46
	v_add_f32_e32 v47, v83, v47
	v_add_f32_e32 v50, v84, v50
	v_mfma_f32_32x32x16_bf16 v[0:15], v[182:185], v[160:163], v[0:15]
	s_waitcnt lgkmcnt(1)
	v_add_f32_e64 v56, v206, -v56
	v_add_f32_e64 v57, v207, -v57
	v_add_f32_e64 v58, v206, -v58
	v_add_f32_e64 v59, v207, -v59
	v_add_f32_e32 v51, v85, v51
	v_pk_add_f32 v[72:73], v[74:75], v[56:57]
	s_waitcnt lgkmcnt(0)
	v_pk_add_f32 v[56:57], v[206:207], v[60:61] neg_lo:[0,1] neg_hi:[0,1]
	v_pk_add_f32 v[74:75], v[76:77], v[58:59]
	v_pk_add_f32 v[58:59], v[206:207], v[62:63] neg_lo:[0,1] neg_hi:[0,1]
	v_mfma_f32_32x32x16_bf16 v[16:31], v[182:185], v[156:159], v[16:31]
	ds_read_b128 v[60:63], v33 offset:352
	ds_read_b128 v[82:85], v33 offset:480
	v_add_f32_e64 v52, v206, -v52
	v_add_f32_e64 v53, v207, -v53
	v_add_f32_e64 v54, v206, -v54
	v_add_f32_e64 v55, v207, -v55
	v_pk_add_f32 v[52:53], v[86:87], v[52:53]
	s_waitcnt lgkmcnt(1)
	v_pk_add_f32 v[60:61], v[206:207], v[60:61] neg_lo:[0,1] neg_hi:[0,1]
	v_pk_add_f32 v[62:63], v[206:207], v[62:63] neg_lo:[0,1] neg_hi:[0,1]
	v_pk_add_f32 v[76:77], v[78:79], v[60:61]
	v_mfma_f32_32x32x16_bf16 v[0:15], v[186:189], v[152:155], v[0:15]
	s_waitcnt lgkmcnt(0)
	v_add_f32_e64 v60, v206, -v82
	v_add_f32_e64 v61, v207, -v83
	v_add_f32_e64 v78, v80, v62
	v_add_f32_e64 v79, v81, v63
	v_pk_add_f32 v[62:63], v[206:207], v[84:85] neg_lo:[0,1] neg_hi:[0,1]
	v_pk_add_f32 v[54:55], v[88:89], v[54:55]
	v_pk_add_f32 v[56:57], v[90:91], v[56:57]
	v_pk_add_f32 v[58:59], v[92:93], v[58:59]
	v_pk_add_f32 v[60:61], v[94:95], v[60:61]
	v_mfma_f32_32x32x16_bf16 v[16:31], v[186:189], v[148:151], v[16:31]
	v_add_f32_e64 v62, v96, v62
	v_add_f32_e64 v63, v97, v63
	v_mfma_f32_32x32x16_bf16 v[0:15], v[128:131], v[198:201], v[0:15]
	v_exp_f32_e32 v64, v48
	v_exp_f32_e32 v65, v49
	v_exp_f32_e32 v66, v66
	v_exp_f32_e32 v67, v67
	v_mfma_f32_32x32x16_bf16 v[16:31], v[128:131], v[106:109], v[16:31]
	v_exp_f32_e32 v68, v68
	v_exp_f32_e32 v69, v69
	v_exp_f32_e32 v70, v70
	v_exp_f32_e32 v71, v71
	v_add_u32_e32 v80, s59, v233
	ds_read_b128 v[172:175], v80
	ds_read_b128 v[164:167], v80 offset:512
	v_mfma_f32_32x32x16_bf16 v[0:15], v[136:139], v[98:101], v[0:15]
	v_exp_f32_e32 v72, v72
	v_exp_f32_e32 v73, v73
	v_exp_f32_e32 v74, v74
	v_exp_f32_e32 v75, v75
	ds_read_b128 v[168:171], v80 offset:2048
	ds_read_b128 v[160:163], v80 offset:2560
	v_mfma_f32_32x32x16_bf16 v[16:31], v[136:139], v[102:105], v[16:31]
	v_exp_f32_e32 v76, v76
	v_exp_f32_e32 v77, v77
	v_exp_f32_e32 v78, v78
	v_exp_f32_e32 v79, v79
	ds_read_b128 v[156:159], v80 offset:4096
	ds_read_b128 v[152:155], v80 offset:4608
	v_mfma_f32_32x32x16_bf16 v[0:15], v[132:135], v[144:147], v[0:15]
	v_exp_f32_e32 v48, v46
	v_exp_f32_e32 v49, v47
	v_exp_f32_e32 v50, v50
	v_exp_f32_e32 v51, v51
	ds_read_b128 v[148:151], v80 offset:6144
	ds_read_b128 v[144:147], v80 offset:6656
	v_mfma_f32_32x32x16_bf16 v[16:31], v[132:135], v[34:37], v[16:31]
	v_exp_f32_e32 v52, v52
	v_exp_f32_e32 v53, v53
	v_exp_f32_e32 v54, v54
	v_exp_f32_e32 v55, v55
	v_mfma_f32_32x32x16_bf16 v[0:15], v[140:143], v[38:41], v[0:15]
	v_exp_f32_e32 v56, v56
	v_exp_f32_e32 v57, v57
	v_exp_f32_e32 v58, v58
	v_exp_f32_e32 v59, v59
	v_mfma_f32_32x32x16_bf16 v[16:31], v[140:143], v[42:45], v[16:31]
	v_exp_f32_e32 v60, v60
	v_exp_f32_e32 v61, v61
	v_exp_f32_e32 v62, v62
	v_exp_f32_e32 v63, v63
	s_add_i32 s14, s59, 0x2000
	s_waitcnt vmcnt(2) lgkmcnt(0)
	s_barrier
	s_cmpk_lg_i32 s59, 0x4000
	s_cselect_b32 s72, s14, 0
	s_add_i32 s19, s19, 2
	v_lshl_add_u64 v[212:213], v[212:213], 0, s[46:47]
	v_lshl_add_u64 v[214:215], v[214:215], 0, s[46:47]
	v_add_u32_e32 v33, 0x200, v33
	s_cmp_ge_i32 s19, s58
	s_mov_b32 s17, s54
	v_mov_b32_e32 v176, v130
	v_mov_b32_e32 v177, v131
	v_mov_b32_e32 v180, v138
	v_mov_b32_e32 v181, v139
	v_mov_b32_e32 v184, v134
	v_mov_b32_e32 v185, v135
	v_mov_b32_e32 v188, v142
	v_mov_b32_e32 v189, v143
	s_cbranch_scc0 .LBB0_871
	s_add_i32 s18, s18, -3
	s_lshl_b64 s[38:39], s[36:37], 10
	s_add_i32 s14, s18, 1
	s_cmp_ge_i32 s14, s58
	s_cbranch_scc0 .LBB0_883
